# stack15: stack12 + K-loop DMA in saddr form and without the s_setprio toggles around the MFMA blocks
# baseline (speedup 1.0000x reference)
; #define WAIT_V0() asm volatile("s_waitcnt vmcnt(0)" ::: "memory")
; #define G_STAGE_A(Ap, buf, kt) do { const char* ab_ = (const char*)(Ap) + (size_t)(kt) * 128; \
;       _Pragma("unroll") for (int i = 0; i < 4; ++i) \
;         __builtin_amdgcn_global_load_lds((const unsigned*)(ab_ + soff[i]), (LDSP unsigned*)(G_SA(buf) + wid * 1024 + i * 8192), 16, 0, 0); } while (0)
; #define G_STAGE_B(Bp, buf, kt) do { const char* bb_ = (const char*)(Bp) + (size_t)(kt) * 128; \
;       _Pragma("unroll") for (int i = 0; i < 4; ++i) \
;         __builtin_amdgcn_global_load_lds((const unsigned*)(bb_ + soff[i]), (LDSP unsigned*)(G_SB(buf) + wid * 1024 + i * 8192), 16, 0, 0); } while (0)
; #define G_RDA(AF, buf, ks, mh) do { _Pragma("unroll") for (int m = 0; m < 4; ++m) AF[m] = *(const LDSP bf16x8*)(G_SA(buf) + aoff + ((mh) * 4 + m) * 2048 + (ks) * 1024); } while (0)
; #define G_RDB(BF, buf, ks) do { _Pragma("unroll") for (int n = 0; n < 4; ++n) BF[n] = *(const LDSP bf16x8*)(G_SB(buf) + boff + n * 2048 + (ks) * 1024); } while (0)
; #define G_MMA(AF, BF, mh) do { __builtin_amdgcn_s_setprio(1); \
;             _Pragma("unroll") for (int m = 0; m < 4; ++m) _Pragma("unroll") for (int n = 0; n < 4; ++n) \
;                 acc[(mh) * 4 + m][n] = __builtin_amdgcn_mfma_f32_16x16x32_bf16(BF[n], AF[m], acc[(mh) * 4 + m][n], 0, 0, 0); \
;             __builtin_amdgcn_s_setprio(0); } while (0)
; template <int EK>
; DI void gemm_stream(const Params& p, int l, const bf16_t* __restrict__ A, const bf16_t* __restrict__ Bt, int M, int N, int K, ldsp_t shm) {
;     ...
;         for (int t = 0; t < nt; ++t) {
;             const int cur = t & 1;
;             G_RDA(Aa, cur, 0, 0); G_RDB(Bk0, cur, 0);
;             if (t + 1 < nt) G_STAGE_B(Bb, cur ^ 1, t + 1);
;             else if (has_next) G_STAGE_B(Bb2, cur ^ 1, 0);
;             G_SB0();
;             if (t > 0) G_MMA(Ab_, Bk1, 1);
;             G_SB0();
;             if (t + 1 < nt) G_STAGE_A(Ab, cur ^ 1, t + 1);
;             else if (has_next) G_STAGE_A(Ab2, cur ^ 1, 0);
;             G_RDA(Ab_, cur, 0, 1);
;             G_MMA(Aa, Bk0, 0); G_SB0();
;             G_RDA(Aa, cur, 1, 0); G_RDB(Bk1, cur, 1);
;             G_MMA(Ab_, Bk0, 1); G_SB0();
;             G_RDA(Ab_, cur, 1, 1);
;             G_MMA(Aa, Bk1, 0); G_SB0();
;             asm volatile("s_waitcnt lgkmcnt(0)" ::: "memory");
;             WAIT_V0(); __syncthreads();
.LBB0_111:
	s_and_b32 s37, s35, 0x10000
	v_add_u32_e32 v221, s37, v218
	v_or_b32_e32 v226, s37, v219
	s_xor_b32 s37, s37, 0x10000
	s_add_u32 s37, s37, s30
	ds_read_b128 v[176:179], v221
	ds_read_b128 v[180:183], v221 offset:2048
	ds_read_b128 v[184:187], v221 offset:4096
	ds_read_b128 v[188:191], v221 offset:6144
	s_add_u32 m0, s37, 0x8000
	ds_read_b128 v[204:207], v226 offset:32768
	global_load_lds_dwordx4 v168, s[64:65]
	s_add_u32 m0, s37, 0xa000
	ds_read_b128 v[210:213], v226 offset:34816
	global_load_lds_dwordx4 v170, s[64:65]
	s_add_u32 m0, s37, 0xc000
	ds_read_b128 v[214:217], v226 offset:36864
	global_load_lds_dwordx4 v172, s[64:65]
	s_add_u32 m0, s37, 0xe000
	ds_read_b128 v[222:225], v226 offset:38912
	global_load_lds_dwordx4 v174, s[64:65]
	v_mfma_f32_16x16x32_bf16 v[128:131], v[64:67], v[156:159], v[128:131]
	v_mfma_f32_16x16x32_bf16 v[124:127], v[68:71], v[156:159], v[124:127]
	v_mfma_f32_16x16x32_bf16 v[120:123], v[76:79], v[156:159], v[120:123]
	v_mfma_f32_16x16x32_bf16 v[116:119], v[72:75], v[156:159], v[116:119]
	v_mfma_f32_16x16x32_bf16 v[112:115], v[64:67], v[152:155], v[112:115]
	v_mfma_f32_16x16x32_bf16 v[108:111], v[68:71], v[152:155], v[108:111]
	v_mfma_f32_16x16x32_bf16 v[104:107], v[76:79], v[152:155], v[104:107]
	v_mfma_f32_16x16x32_bf16 v[100:103], v[72:75], v[152:155], v[100:103]
	v_mfma_f32_16x16x32_bf16 v[96:99], v[64:67], v[148:151], v[96:99]
	v_mfma_f32_16x16x32_bf16 v[92:95], v[68:71], v[148:151], v[92:95]
	v_mfma_f32_16x16x32_bf16 v[88:91], v[76:79], v[148:151], v[88:91]
	v_mfma_f32_16x16x32_bf16 v[84:87], v[72:75], v[148:151], v[84:87]
	v_mfma_f32_16x16x32_bf16 v[132:135], v[64:67], v[144:147], v[132:135]
	v_mfma_f32_16x16x32_bf16 v[136:139], v[68:71], v[144:147], v[136:139]
	v_mfma_f32_16x16x32_bf16 v[140:143], v[76:79], v[144:147], v[140:143]
	v_mfma_f32_16x16x32_bf16 v[80:83], v[72:75], v[144:147], v[80:83]
	s_add_u32 m0, s37, 0x0
	s_nop 0
	global_load_lds_dwordx4 v168, s[52:53]
	s_add_u32 m0, s37, 0x2000
	s_nop 0
	global_load_lds_dwordx4 v170, s[52:53]
	s_add_u32 m0, s37, 0x4000
	s_nop 0
	global_load_lds_dwordx4 v172, s[52:53]
	s_add_u32 m0, s37, 0x6000
	s_nop 0
	global_load_lds_dwordx4 v174, s[52:53]
	ds_read_b128 v[144:147], v221 offset:8192
	ds_read_b128 v[148:151], v221 offset:10240
	ds_read_b128 v[152:155], v221 offset:12288
	ds_read_b128 v[156:159], v221 offset:14336
	s_waitcnt lgkmcnt(4)
	v_mfma_f32_16x16x32_bf16 v[60:63], v[204:207], v[176:179], v[60:63]
	v_mfma_f32_16x16x32_bf16 v[56:59], v[210:213], v[176:179], v[56:59]
	v_mfma_f32_16x16x32_bf16 v[52:55], v[214:217], v[176:179], v[52:55]
	v_mfma_f32_16x16x32_bf16 v[48:51], v[222:225], v[176:179], v[48:51]
	v_mfma_f32_16x16x32_bf16 v[44:47], v[204:207], v[180:183], v[44:47]
	v_mfma_f32_16x16x32_bf16 v[40:43], v[210:213], v[180:183], v[40:43]
	v_mfma_f32_16x16x32_bf16 v[36:39], v[214:217], v[180:183], v[36:39]
	v_mfma_f32_16x16x32_bf16 v[32:35], v[222:225], v[180:183], v[32:35]
	v_mfma_f32_16x16x32_bf16 v[28:31], v[204:207], v[184:187], v[28:31]
	v_mfma_f32_16x16x32_bf16 v[24:27], v[210:213], v[184:187], v[24:27]
	v_mfma_f32_16x16x32_bf16 v[20:23], v[214:217], v[184:187], v[20:23]
	v_mfma_f32_16x16x32_bf16 v[16:19], v[222:225], v[184:187], v[16:19]
	v_mfma_f32_16x16x32_bf16 v[12:15], v[204:207], v[188:191], v[12:15]
	v_mfma_f32_16x16x32_bf16 v[8:11], v[210:213], v[188:191], v[8:11]
	v_mfma_f32_16x16x32_bf16 v[4:7], v[214:217], v[188:191], v[4:7]
	v_mfma_f32_16x16x32_bf16 v[0:3], v[222:225], v[188:191], v[0:3]
	ds_read_b128 v[176:179], v221 offset:1024
	ds_read_b128 v[180:183], v221 offset:3072
	ds_read_b128 v[184:187], v221 offset:5120
	ds_read_b128 v[188:191], v221 offset:7168
	ds_read_b128 v[64:67], v226 offset:33792
	ds_read_b128 v[68:71], v226 offset:35840
	ds_read_b128 v[76:79], v226 offset:37888
	ds_read_b128 v[72:75], v226 offset:39936
	s_waitcnt lgkmcnt(8)
	v_mfma_f32_16x16x32_bf16 v[128:131], v[204:207], v[144:147], v[128:131]
	v_mfma_f32_16x16x32_bf16 v[124:127], v[210:213], v[144:147], v[124:127]
	v_mfma_f32_16x16x32_bf16 v[120:123], v[214:217], v[144:147], v[120:123]
	v_mfma_f32_16x16x32_bf16 v[116:119], v[222:225], v[144:147], v[116:119]
	v_mfma_f32_16x16x32_bf16 v[112:115], v[204:207], v[148:151], v[112:115]
	v_mfma_f32_16x16x32_bf16 v[108:111], v[210:213], v[148:151], v[108:111]
	v_mfma_f32_16x16x32_bf16 v[104:107], v[214:217], v[148:151], v[104:107]
	v_mfma_f32_16x16x32_bf16 v[100:103], v[222:225], v[148:151], v[100:103]
	v_mfma_f32_16x16x32_bf16 v[96:99], v[204:207], v[152:155], v[96:99]
	v_mfma_f32_16x16x32_bf16 v[92:95], v[210:213], v[152:155], v[92:95]
	v_mfma_f32_16x16x32_bf16 v[88:91], v[214:217], v[152:155], v[88:91]
	v_mfma_f32_16x16x32_bf16 v[84:87], v[222:225], v[152:155], v[84:87]
	v_mfma_f32_16x16x32_bf16 v[132:135], v[204:207], v[156:159], v[132:135]
	v_mfma_f32_16x16x32_bf16 v[136:139], v[210:213], v[156:159], v[136:139]
	v_mfma_f32_16x16x32_bf16 v[140:143], v[214:217], v[156:159], v[140:143]
	v_mfma_f32_16x16x32_bf16 v[80:83], v[222:225], v[156:159], v[80:83]
	ds_read_b128 v[156:159], v221 offset:9216
	ds_read_b128 v[152:155], v221 offset:11264
	ds_read_b128 v[148:151], v221 offset:13312
	ds_read_b128 v[144:147], v221 offset:15360
	s_waitcnt lgkmcnt(4)
	v_mfma_f32_16x16x32_bf16 v[60:63], v[64:67], v[176:179], v[60:63]
	v_mfma_f32_16x16x32_bf16 v[56:59], v[68:71], v[176:179], v[56:59]
	v_mfma_f32_16x16x32_bf16 v[52:55], v[76:79], v[176:179], v[52:55]
	v_mfma_f32_16x16x32_bf16 v[48:51], v[72:75], v[176:179], v[48:51]
	v_mfma_f32_16x16x32_bf16 v[44:47], v[64:67], v[180:183], v[44:47]
	v_mfma_f32_16x16x32_bf16 v[40:43], v[68:71], v[180:183], v[40:43]
	v_mfma_f32_16x16x32_bf16 v[36:39], v[76:79], v[180:183], v[36:39]
	v_mfma_f32_16x16x32_bf16 v[32:35], v[72:75], v[180:183], v[32:35]
	v_mfma_f32_16x16x32_bf16 v[28:31], v[64:67], v[184:187], v[28:31]
	v_mfma_f32_16x16x32_bf16 v[24:27], v[68:71], v[184:187], v[24:27]
	v_mfma_f32_16x16x32_bf16 v[20:23], v[76:79], v[184:187], v[20:23]
	v_mfma_f32_16x16x32_bf16 v[16:19], v[72:75], v[184:187], v[16:19]
	v_mfma_f32_16x16x32_bf16 v[12:15], v[64:67], v[188:191], v[12:15]
	v_mfma_f32_16x16x32_bf16 v[8:11], v[68:71], v[188:191], v[8:11]
	v_mfma_f32_16x16x32_bf16 v[4:7], v[76:79], v[188:191], v[4:7]
	v_mfma_f32_16x16x32_bf16 v[0:3], v[72:75], v[188:191], v[0:3]
	s_waitcnt lgkmcnt(0)
	s_add_u32 s52, s52, 0x80
	s_addc_u32 s53, s53, 0
	s_add_u32 s64, s64, 0x80
	s_addc_u32 s65, s65, 0
	s_add_u32 s4, s4, 0x80
	s_addc_u32 s5, s5, 0
	s_add_i32 s35, s35, 0x10000
	s_cmpk_eq_i32 s4, 0x700
	s_waitcnt vmcnt(0)
	s_barrier
; #define WAIT_V0() asm volatile("s_waitcnt vmcnt(0)" ::: "memory")
; #define G_STAGE_B(Bp, buf, kt) do { const char* bb_ = (const char*)(Bp) + (size_t)(kt) * 128; \
;       _Pragma("unroll") for (int i = 0; i < 4; ++i) \
;         __builtin_amdgcn_global_load_lds((const unsigned*)(bb_ + soff[i]), (LDSP unsigned*)(G_SB(buf) + wid * 1024 + i * 8192), 16, 0, 0); } while (0)
; #define G_RDA(AF, buf, ks, mh) do { _Pragma("unroll") for (int m = 0; m < 4; ++m) AF[m] = *(const LDSP bf16x8*)(G_SA(buf) + aoff + ((mh) * 4 + m) * 2048 + (ks) * 1024); } while (0)
; #define G_RDB(BF, buf, ks) do { _Pragma("unroll") for (int n = 0; n < 4; ++n) BF[n] = *(const LDSP bf16x8*)(G_SB(buf) + boff + n * 2048 + (ks) * 1024); } while (0)
; template <int EK>
; DI void gemm_stream(const Params& p, int l, const bf16_t* __restrict__ A, const bf16_t* __restrict__ Bt, int M, int N, int K, ldsp_t shm) {
;     ...
;         for (int t = 0; t < nt; ++t) {
;             const int cur = t & 1;
;             G_RDA(Aa, cur, 0, 0); G_RDB(Bk0, cur, 0);
;             if (t + 1 < nt) G_STAGE_B(Bb, cur ^ 1, t + 1);
;             else if (has_next) G_STAGE_B(Bb2, cur ^ 1, 0);
;     ...
;             WAIT_V0(); __syncthreads();
	s_cbranch_scc0 .LBB0_111
	v_readlane_b32 s52, v255, 12
	v_readlane_b32 s53, v255, 13
	v_readlane_b32 s64, v255, 14
	v_readlane_b32 s65, v255, 15
	v_readlane_b32 s30, v255, 16
	v_add_u32_e32 v160, 0x10000, v218
	v_add_u32_e32 v161, 0x10800, v218
	ds_read_b128 v[188:191], v160
	ds_read_b128 v[180:183], v161
	v_add_u32_e32 v160, 0x11000, v218
	v_add_u32_e32 v161, 0x11800, v218
	ds_read_b128 v[184:187], v160
	ds_read_b128 v[176:179], v161
	v_or_b32_e32 v160, 0x18000, v219
	v_add_u32_e32 v164, 0x18800, v219
	v_add_u32_e32 v168, 0x19000, v219
	v_add_u32_e32 v172, 0x19800, v219
	ds_read_b128 v[160:163], v160
	ds_read_b128 v[164:167], v164
	ds_read_b128 v[168:171], v168
	ds_read_b128 v[172:175], v172
	s_ashr_i32 s37, s36, 31
	v_cndmask_b32_e64 v200, 0, 1, s[42:43]
	v_cmp_ne_u32_e64 s[4:5], 1, v200
	s_andn2_b64 vcc, exec, s[42:43]
	s_lshl_b64 s[38:39], s[36:37], 19
	s_cbranch_vccnz .LBB0_114
	s_add_u32 s40, s9, s38
	v_add_u32_e32 v212, 0x8000, v220
	s_addc_u32 s41, s45, s39
	v_add_u32_e32 v215, 0xa000, v220
	v_readfirstlane_b32 s35, v212
	v_lshl_add_u64 v[200:201], s[40:41], 0, v[192:193]
	v_add_u32_e32 v214, 0xc000, v220
	s_mov_b32 m0, s35
	v_readfirstlane_b32 s35, v215
	v_lshl_add_u64 v[204:205], s[40:41], 0, v[194:195]
	v_add_u32_e32 v213, 0xe000, v220
	global_load_lds_dwordx4 v[200:201], off
	s_mov_b32 m0, s35
	v_readfirstlane_b32 s35, v214
	v_lshl_add_u64 v[206:207], s[40:41], 0, v[196:197]
	global_load_lds_dwordx4 v[204:205], off
	s_mov_b32 m0, s35
	v_readfirstlane_b32 s35, v213
	v_lshl_add_u64 v[210:211], s[40:41], 0, v[198:199]
	global_load_lds_dwordx4 v[206:207], off
	s_mov_b32 m0, s35
	s_nop 0
	global_load_lds_dwordx4 v[210:211], off

; #define WAIT_V0() asm volatile("s_waitcnt vmcnt(0)" ::: "memory")
; #define G_STAGE_A(Ap, buf, kt) do { const char* ab_ = (const char*)(Ap) + (size_t)(kt) * 128; \
;       _Pragma("unroll") for (int i = 0; i < 4; ++i) \
;         __builtin_amdgcn_global_load_lds((const unsigned*)(ab_ + soff[i]), (LDSP unsigned*)(G_SA(buf) + wid * 1024 + i * 8192), 16, 0, 0); } while (0)
; #define G_STAGE_B(Bp, buf, kt) do { const char* bb_ = (const char*)(Bp) + (size_t)(kt) * 128; \
;       _Pragma("unroll") for (int i = 0; i < 4; ++i) \
;         __builtin_amdgcn_global_load_lds((const unsigned*)(bb_ + soff[i]), (LDSP unsigned*)(G_SB(buf) + wid * 1024 + i * 8192), 16, 0, 0); } while (0)
; #define G_RDA(AF, buf, ks, mh) do { _Pragma("unroll") for (int m = 0; m < 4; ++m) AF[m] = *(const LDSP bf16x8*)(G_SA(buf) + aoff + ((mh) * 4 + m) * 2048 + (ks) * 1024); } while (0)
; #define G_RDB(BF, buf, ks) do { _Pragma("unroll") for (int n = 0; n < 4; ++n) BF[n] = *(const LDSP bf16x8*)(G_SB(buf) + boff + n * 2048 + (ks) * 1024); } while (0)
; #define G_MMA(AF, BF, mh) do { __builtin_amdgcn_s_setprio(1); \
;             _Pragma("unroll") for (int m = 0; m < 4; ++m) _Pragma("unroll") for (int n = 0; n < 4; ++n) \
;                 acc[(mh) * 4 + m][n] = __builtin_amdgcn_mfma_f32_16x16x32_bf16(BF[n], AF[m], acc[(mh) * 4 + m][n], 0, 0, 0); \
;             __builtin_amdgcn_s_setprio(0); } while (0)
; template <int EK>
; DI void gemm_stream(const Params& p, int l, const bf16_t* __restrict__ A, const bf16_t* __restrict__ Bt, int M, int N, int K, ldsp_t shm) {
;     ...
;         for (int t = 0; t < nt; ++t) {
;             const int cur = t & 1;
;             G_RDA(Aa, cur, 0, 0); G_RDB(Bk0, cur, 0);
;             if (t + 1 < nt) G_STAGE_B(Bb, cur ^ 1, t + 1);
;             else if (has_next) G_STAGE_B(Bb2, cur ^ 1, 0);
;             G_SB0();
;             if (t > 0) G_MMA(Ab_, Bk1, 1);
;             G_SB0();
;             if (t + 1 < nt) G_STAGE_A(Ab, cur ^ 1, t + 1);
;             else if (has_next) G_STAGE_A(Ab2, cur ^ 1, 0);
;             G_RDA(Ab_, cur, 0, 1);
;             G_MMA(Aa, Bk0, 0); G_SB0();
;             G_RDA(Aa, cur, 1, 0); G_RDB(Bk1, cur, 1);
;             G_MMA(Ab_, Bk0, 1); G_SB0();
;             G_RDA(Ab_, cur, 1, 1);
;             G_MMA(Aa, Bk1, 0); G_SB0();
;             asm volatile("s_waitcnt lgkmcnt(0)" ::: "memory");
;             WAIT_V0(); __syncthreads();
.LBB0_132:
	s_and_b32 s43, s41, 0x10000
	v_add_u32_e32 v221, s43, v218
	v_or_b32_e32 v226, s43, v219
	s_xor_b32 s43, s43, 0x10000
	s_add_u32 s43, s43, s30
	ds_read_b128 v[176:179], v221
	ds_read_b128 v[180:183], v221 offset:2048
	ds_read_b128 v[184:187], v221 offset:4096
	ds_read_b128 v[188:191], v221 offset:6144
	s_add_u32 m0, s43, 0x8000
	ds_read_b128 v[204:207], v226 offset:32768
	global_load_lds_dwordx4 v168, s[64:65]
	s_add_u32 m0, s43, 0xa000
	ds_read_b128 v[210:213], v226 offset:34816
	global_load_lds_dwordx4 v170, s[64:65]
	s_add_u32 m0, s43, 0xc000
	ds_read_b128 v[214:217], v226 offset:36864
	global_load_lds_dwordx4 v172, s[64:65]
	s_add_u32 m0, s43, 0xe000
	ds_read_b128 v[222:225], v226 offset:38912
	global_load_lds_dwordx4 v174, s[64:65]
	v_mfma_f32_16x16x32_bf16 v[140:143], v[64:67], v[156:159], v[140:143]
	v_mfma_f32_16x16x32_bf16 v[136:139], v[68:71], v[156:159], v[136:139]
	v_mfma_f32_16x16x32_bf16 v[132:135], v[72:75], v[156:159], v[132:135]
	v_mfma_f32_16x16x32_bf16 v[128:131], v[76:79], v[156:159], v[128:131]
	v_mfma_f32_16x16x32_bf16 v[124:127], v[64:67], v[152:155], v[124:127]
	v_mfma_f32_16x16x32_bf16 v[120:123], v[68:71], v[152:155], v[120:123]
	v_mfma_f32_16x16x32_bf16 v[116:119], v[72:75], v[152:155], v[116:119]
	v_mfma_f32_16x16x32_bf16 v[112:115], v[76:79], v[152:155], v[112:115]
	v_mfma_f32_16x16x32_bf16 v[108:111], v[64:67], v[148:151], v[108:111]
	v_mfma_f32_16x16x32_bf16 v[104:107], v[68:71], v[148:151], v[104:107]
	v_mfma_f32_16x16x32_bf16 v[100:103], v[72:75], v[148:151], v[100:103]
	v_mfma_f32_16x16x32_bf16 v[96:99], v[76:79], v[148:151], v[96:99]
	v_mfma_f32_16x16x32_bf16 v[92:95], v[64:67], v[144:147], v[92:95]
	v_mfma_f32_16x16x32_bf16 v[88:91], v[68:71], v[144:147], v[88:91]
	v_mfma_f32_16x16x32_bf16 v[84:87], v[72:75], v[144:147], v[84:87]
	v_mfma_f32_16x16x32_bf16 v[80:83], v[76:79], v[144:147], v[80:83]
	s_add_u32 m0, s43, 0x0
	s_nop 0
	global_load_lds_dwordx4 v168, s[52:53]
	s_add_u32 m0, s43, 0x2000
	s_nop 0
	global_load_lds_dwordx4 v170, s[52:53]
	s_add_u32 m0, s43, 0x4000
	s_nop 0
	global_load_lds_dwordx4 v172, s[52:53]
	s_add_u32 m0, s43, 0x6000
	s_nop 0
	global_load_lds_dwordx4 v174, s[52:53]
	ds_read_b128 v[144:147], v221 offset:8192
	ds_read_b128 v[148:151], v221 offset:10240
	ds_read_b128 v[152:155], v221 offset:12288
	ds_read_b128 v[156:159], v221 offset:14336
	s_waitcnt lgkmcnt(4)
	v_mfma_f32_16x16x32_bf16 v[0:3], v[204:207], v[176:179], v[0:3]
	v_mfma_f32_16x16x32_bf16 v[4:7], v[210:213], v[176:179], v[4:7]
	v_mfma_f32_16x16x32_bf16 v[8:11], v[214:217], v[176:179], v[8:11]
	v_mfma_f32_16x16x32_bf16 v[12:15], v[222:225], v[176:179], v[12:15]
	v_mfma_f32_16x16x32_bf16 v[16:19], v[204:207], v[180:183], v[16:19]
	v_mfma_f32_16x16x32_bf16 v[20:23], v[210:213], v[180:183], v[20:23]
	v_mfma_f32_16x16x32_bf16 v[24:27], v[214:217], v[180:183], v[24:27]
	v_mfma_f32_16x16x32_bf16 v[28:31], v[222:225], v[180:183], v[28:31]
	v_mfma_f32_16x16x32_bf16 v[32:35], v[204:207], v[184:187], v[32:35]
	v_mfma_f32_16x16x32_bf16 v[36:39], v[210:213], v[184:187], v[36:39]
	v_mfma_f32_16x16x32_bf16 v[40:43], v[214:217], v[184:187], v[40:43]
	v_mfma_f32_16x16x32_bf16 v[44:47], v[222:225], v[184:187], v[44:47]
	v_mfma_f32_16x16x32_bf16 v[48:51], v[204:207], v[188:191], v[48:51]
	v_mfma_f32_16x16x32_bf16 v[52:55], v[210:213], v[188:191], v[52:55]
	v_mfma_f32_16x16x32_bf16 v[56:59], v[214:217], v[188:191], v[56:59]
	v_mfma_f32_16x16x32_bf16 v[60:63], v[222:225], v[188:191], v[60:63]
	ds_read_b128 v[176:179], v221 offset:1024
	ds_read_b128 v[180:183], v221 offset:3072
	ds_read_b128 v[184:187], v221 offset:5120
	ds_read_b128 v[188:191], v221 offset:7168
	ds_read_b128 v[64:67], v226 offset:33792
	ds_read_b128 v[68:71], v226 offset:35840
	ds_read_b128 v[72:75], v226 offset:37888
	ds_read_b128 v[76:79], v226 offset:39936
	s_waitcnt lgkmcnt(8)
	v_mfma_f32_16x16x32_bf16 v[140:143], v[204:207], v[144:147], v[140:143]
	v_mfma_f32_16x16x32_bf16 v[136:139], v[210:213], v[144:147], v[136:139]
	v_mfma_f32_16x16x32_bf16 v[132:135], v[214:217], v[144:147], v[132:135]
	v_mfma_f32_16x16x32_bf16 v[128:131], v[222:225], v[144:147], v[128:131]
	v_mfma_f32_16x16x32_bf16 v[124:127], v[204:207], v[148:151], v[124:127]
	v_mfma_f32_16x16x32_bf16 v[120:123], v[210:213], v[148:151], v[120:123]
	v_mfma_f32_16x16x32_bf16 v[116:119], v[214:217], v[148:151], v[116:119]
	v_mfma_f32_16x16x32_bf16 v[112:115], v[222:225], v[148:151], v[112:115]
	v_mfma_f32_16x16x32_bf16 v[108:111], v[204:207], v[152:155], v[108:111]
	v_mfma_f32_16x16x32_bf16 v[104:107], v[210:213], v[152:155], v[104:107]
	v_mfma_f32_16x16x32_bf16 v[100:103], v[214:217], v[152:155], v[100:103]
	v_mfma_f32_16x16x32_bf16 v[96:99], v[222:225], v[152:155], v[96:99]
	v_mfma_f32_16x16x32_bf16 v[92:95], v[204:207], v[156:159], v[92:95]
	v_mfma_f32_16x16x32_bf16 v[88:91], v[210:213], v[156:159], v[88:91]
	v_mfma_f32_16x16x32_bf16 v[84:87], v[214:217], v[156:159], v[84:87]
	v_mfma_f32_16x16x32_bf16 v[80:83], v[222:225], v[156:159], v[80:83]
	ds_read_b128 v[156:159], v221 offset:9216
	ds_read_b128 v[152:155], v221 offset:11264
	ds_read_b128 v[148:151], v221 offset:13312
	ds_read_b128 v[144:147], v221 offset:15360
	s_waitcnt lgkmcnt(4)
	v_mfma_f32_16x16x32_bf16 v[0:3], v[64:67], v[176:179], v[0:3]
	v_mfma_f32_16x16x32_bf16 v[4:7], v[68:71], v[176:179], v[4:7]
	v_mfma_f32_16x16x32_bf16 v[8:11], v[72:75], v[176:179], v[8:11]
	v_mfma_f32_16x16x32_bf16 v[12:15], v[76:79], v[176:179], v[12:15]
	v_mfma_f32_16x16x32_bf16 v[16:19], v[64:67], v[180:183], v[16:19]
	v_mfma_f32_16x16x32_bf16 v[20:23], v[68:71], v[180:183], v[20:23]
	v_mfma_f32_16x16x32_bf16 v[24:27], v[72:75], v[180:183], v[24:27]
	v_mfma_f32_16x16x32_bf16 v[28:31], v[76:79], v[180:183], v[28:31]
	v_mfma_f32_16x16x32_bf16 v[32:35], v[64:67], v[184:187], v[32:35]
	v_mfma_f32_16x16x32_bf16 v[36:39], v[68:71], v[184:187], v[36:39]
	v_mfma_f32_16x16x32_bf16 v[40:43], v[72:75], v[184:187], v[40:43]
	v_mfma_f32_16x16x32_bf16 v[44:47], v[76:79], v[184:187], v[44:47]
	v_mfma_f32_16x16x32_bf16 v[48:51], v[64:67], v[188:191], v[48:51]
	v_mfma_f32_16x16x32_bf16 v[52:55], v[68:71], v[188:191], v[52:55]
	v_mfma_f32_16x16x32_bf16 v[56:59], v[72:75], v[188:191], v[56:59]
	v_mfma_f32_16x16x32_bf16 v[60:63], v[76:79], v[188:191], v[60:63]
	s_waitcnt lgkmcnt(0)
	s_add_u32 s52, s52, 0x80
	s_addc_u32 s53, s53, 0
	s_add_u32 s64, s64, 0x80
	s_addc_u32 s65, s65, 0
	s_add_u32 s6, s6, 0x80
	s_addc_u32 s7, s7, 0
	s_add_i32 s41, s41, 0x10000
	s_cmpk_eq_i32 s6, 0x700
	s_waitcnt vmcnt(0)
	s_barrier
; #define WAIT_V0() asm volatile("s_waitcnt vmcnt(0)" ::: "memory")
; #define G_STAGE_B(Bp, buf, kt) do { const char* bb_ = (const char*)(Bp) + (size_t)(kt) * 128; \
;       _Pragma("unroll") for (int i = 0; i < 4; ++i) \
;         __builtin_amdgcn_global_load_lds((const unsigned*)(bb_ + soff[i]), (LDSP unsigned*)(G_SB(buf) + wid * 1024 + i * 8192), 16, 0, 0); } while (0)
; #define G_RDA(AF, buf, ks, mh) do { _Pragma("unroll") for (int m = 0; m < 4; ++m) AF[m] = *(const LDSP bf16x8*)(G_SA(buf) + aoff + ((mh) * 4 + m) * 2048 + (ks) * 1024); } while (0)
; #define G_RDB(BF, buf, ks) do { _Pragma("unroll") for (int n = 0; n < 4; ++n) BF[n] = *(const LDSP bf16x8*)(G_SB(buf) + boff + n * 2048 + (ks) * 1024); } while (0)
; template <int EK>
; DI void gemm_stream(const Params& p, int l, const bf16_t* __restrict__ A, const bf16_t* __restrict__ Bt, int M, int N, int K, ldsp_t shm) {
;     ...
;         for (int t = 0; t < nt; ++t) {
;             const int cur = t & 1;
;             G_RDA(Aa, cur, 0, 0); G_RDB(Bk0, cur, 0);
;             if (t + 1 < nt) G_STAGE_B(Bb, cur ^ 1, t + 1);
;             else if (has_next) G_STAGE_B(Bb2, cur ^ 1, 0);
;     ...
;             WAIT_V0(); __syncthreads();
	s_cbranch_scc0 .LBB0_132
	v_readlane_b32 s52, v255, 12
	v_readlane_b32 s53, v255, 13
	v_readlane_b32 s64, v255, 14
	v_readlane_b32 s65, v255, 15
	v_readlane_b32 s30, v255, 16
	v_add_u32_e32 v160, 0x10000, v218
	v_add_u32_e32 v161, 0x10800, v218
	ds_read_b128 v[188:191], v160
	ds_read_b128 v[180:183], v161
	v_add_u32_e32 v160, 0x11000, v218
	v_add_u32_e32 v161, 0x11800, v218
	ds_read_b128 v[184:187], v160
	ds_read_b128 v[176:179], v161
	v_or_b32_e32 v160, 0x18000, v219
	v_add_u32_e32 v164, 0x18800, v219
	v_add_u32_e32 v168, 0x19000, v219
	v_add_u32_e32 v172, 0x19800, v219
	ds_read_b128 v[160:163], v160
	ds_read_b128 v[164:167], v164
	ds_read_b128 v[168:171], v168
	ds_read_b128 v[172:175], v172
	s_ashr_i32 s43, s42, 31
	v_cndmask_b32_e64 v200, 0, 1, s[38:39]
	v_cmp_ne_u32_e64 s[6:7], 1, v200
	s_andn2_b64 vcc, exec, s[38:39]
	s_lshl_b64 s[46:47], s[42:43], 19
	s_cbranch_vccnz .LBB0_135
	s_add_u32 s38, s93, s46
	s_addc_u32 s39, s98, s47
	v_add_u32_e32 v212, 0x8000, v220
	v_lshl_add_u64 v[200:201], s[38:39], 0, v[192:193]
	v_lshl_add_u64 v[204:205], s[38:39], 0, v[194:195]
	v_lshl_add_u64 v[206:207], s[38:39], 0, v[196:197]
	v_lshl_add_u64 v[210:211], s[38:39], 0, v[198:199]
	v_add_u32_e32 v215, 0xa000, v220
	v_readfirstlane_b32 s38, v212
	v_add_u32_e32 v214, 0xc000, v220
	s_mov_b32 m0, s38
	v_readfirstlane_b32 s38, v215
	v_add_u32_e32 v213, 0xe000, v220
	global_load_lds_dwordx4 v[200:201], off
	s_mov_b32 m0, s38
	v_readfirstlane_b32 s38, v214
	global_load_lds_dwordx4 v[204:205], off
	s_mov_b32 m0, s38
	v_readfirstlane_b32 s38, v213
	global_load_lds_dwordx4 v[206:207], off
	s_mov_b32 m0, s38
	s_nop 0
	global_load_lds_dwordx4 v[210:211], off

; #define WAIT_V0() asm volatile("s_waitcnt vmcnt(0)" ::: "memory")
; #define G_STAGE_A(Ap, buf, kt) do { const char* ab_ = (const char*)(Ap) + (size_t)(kt) * 128; \
;       _Pragma("unroll") for (int i = 0; i < 4; ++i) \
;         __builtin_amdgcn_global_load_lds((const unsigned*)(ab_ + soff[i]), (LDSP unsigned*)(G_SA(buf) + wid * 1024 + i * 8192), 16, 0, 0); } while (0)
; #define G_STAGE_B(Bp, buf, kt) do { const char* bb_ = (const char*)(Bp) + (size_t)(kt) * 128; \
;       _Pragma("unroll") for (int i = 0; i < 4; ++i) \
;         __builtin_amdgcn_global_load_lds((const unsigned*)(bb_ + soff[i]), (LDSP unsigned*)(G_SB(buf) + wid * 1024 + i * 8192), 16, 0, 0); } while (0)
; #define G_RDA(AF, buf, ks, mh) do { _Pragma("unroll") for (int m = 0; m < 4; ++m) AF[m] = *(const LDSP bf16x8*)(G_SA(buf) + aoff + ((mh) * 4 + m) * 2048 + (ks) * 1024); } while (0)
; #define G_RDB(BF, buf, ks) do { _Pragma("unroll") for (int n = 0; n < 4; ++n) BF[n] = *(const LDSP bf16x8*)(G_SB(buf) + boff + n * 2048 + (ks) * 1024); } while (0)
; #define G_MMA(AF, BF, mh) do { __builtin_amdgcn_s_setprio(1); \
;             _Pragma("unroll") for (int m = 0; m < 4; ++m) _Pragma("unroll") for (int n = 0; n < 4; ++n) \
;                 acc[(mh) * 4 + m][n] = __builtin_amdgcn_mfma_f32_16x16x32_bf16(BF[n], AF[m], acc[(mh) * 4 + m][n], 0, 0, 0); \
;             __builtin_amdgcn_s_setprio(0); } while (0)
; template <int EK>
; DI void gemm_stream(const Params& p, int l, const bf16_t* __restrict__ A, const bf16_t* __restrict__ Bt, int M, int N, int K, ldsp_t shm) {
;     ...
;         for (int t = 0; t < nt; ++t) {
;             const int cur = t & 1;
;             G_RDA(Aa, cur, 0, 0); G_RDB(Bk0, cur, 0);
;             if (t + 1 < nt) G_STAGE_B(Bb, cur ^ 1, t + 1);
;             else if (has_next) G_STAGE_B(Bb2, cur ^ 1, 0);
;             G_SB0();
;             if (t > 0) G_MMA(Ab_, Bk1, 1);
;             G_SB0();
;             if (t + 1 < nt) G_STAGE_A(Ab, cur ^ 1, t + 1);
;             else if (has_next) G_STAGE_A(Ab2, cur ^ 1, 0);
;             G_RDA(Ab_, cur, 0, 1);
;             G_MMA(Aa, Bk0, 0); G_SB0();
;             G_RDA(Aa, cur, 1, 0); G_RDB(Bk1, cur, 1);
;             G_MMA(Ab_, Bk0, 1); G_SB0();
;             G_RDA(Ab_, cur, 1, 1);
;             G_MMA(Aa, Bk1, 0); G_SB0();
;             asm volatile("s_waitcnt lgkmcnt(0)" ::: "memory");
;             WAIT_V0(); __syncthreads();
.LBB0_191:
	s_and_b32 s6, s43, 0x10000
	v_add_u32_e32 v221, s6, v218
	v_or_b32_e32 v226, s6, v219
	s_xor_b32 s6, s6, 0x10000
	s_add_u32 s6, s6, s30
	ds_read_b128 v[176:179], v221
	ds_read_b128 v[180:183], v221 offset:2048
	ds_read_b128 v[184:187], v221 offset:4096
	ds_read_b128 v[188:191], v221 offset:6144
	s_add_u32 m0, s6, 0x8000
	ds_read_b128 v[204:207], v226 offset:32768
	global_load_lds_dwordx4 v168, s[64:65]
	s_add_u32 m0, s6, 0xa000
	ds_read_b128 v[210:213], v226 offset:34816
	global_load_lds_dwordx4 v170, s[64:65]
	s_add_u32 m0, s6, 0xc000
	ds_read_b128 v[214:217], v226 offset:36864
	global_load_lds_dwordx4 v172, s[64:65]
	s_add_u32 m0, s6, 0xe000
	ds_read_b128 v[222:225], v226 offset:38912
	global_load_lds_dwordx4 v174, s[64:65]
	v_mfma_f32_16x16x32_bf16 v[140:143], v[64:67], v[156:159], v[140:143]
	v_mfma_f32_16x16x32_bf16 v[136:139], v[68:71], v[156:159], v[136:139]
	v_mfma_f32_16x16x32_bf16 v[132:135], v[72:75], v[156:159], v[132:135]
	v_mfma_f32_16x16x32_bf16 v[128:131], v[76:79], v[156:159], v[128:131]
	v_mfma_f32_16x16x32_bf16 v[124:127], v[64:67], v[152:155], v[124:127]
	v_mfma_f32_16x16x32_bf16 v[120:123], v[68:71], v[152:155], v[120:123]
	v_mfma_f32_16x16x32_bf16 v[116:119], v[72:75], v[152:155], v[116:119]
	v_mfma_f32_16x16x32_bf16 v[112:115], v[76:79], v[152:155], v[112:115]
	v_mfma_f32_16x16x32_bf16 v[108:111], v[64:67], v[148:151], v[108:111]
	v_mfma_f32_16x16x32_bf16 v[104:107], v[68:71], v[148:151], v[104:107]
	v_mfma_f32_16x16x32_bf16 v[100:103], v[72:75], v[148:151], v[100:103]
	v_mfma_f32_16x16x32_bf16 v[96:99], v[76:79], v[148:151], v[96:99]
	v_mfma_f32_16x16x32_bf16 v[92:95], v[64:67], v[144:147], v[92:95]
	v_mfma_f32_16x16x32_bf16 v[88:91], v[68:71], v[144:147], v[88:91]
	v_mfma_f32_16x16x32_bf16 v[84:87], v[72:75], v[144:147], v[84:87]
	v_mfma_f32_16x16x32_bf16 v[80:83], v[76:79], v[144:147], v[80:83]
	s_add_u32 m0, s6, 0x0
	s_nop 0
	global_load_lds_dwordx4 v168, s[52:53]
	s_add_u32 m0, s6, 0x2000
	s_nop 0
	global_load_lds_dwordx4 v170, s[52:53]
	s_add_u32 m0, s6, 0x4000
	s_nop 0
	global_load_lds_dwordx4 v172, s[52:53]
	s_add_u32 m0, s6, 0x6000
	s_nop 0
	global_load_lds_dwordx4 v174, s[52:53]
	ds_read_b128 v[144:147], v221 offset:8192
	ds_read_b128 v[148:151], v221 offset:10240
	ds_read_b128 v[152:155], v221 offset:12288
	ds_read_b128 v[156:159], v221 offset:14336
	s_waitcnt lgkmcnt(4)
	v_mfma_f32_16x16x32_bf16 v[0:3], v[204:207], v[176:179], v[0:3]
	v_mfma_f32_16x16x32_bf16 v[4:7], v[210:213], v[176:179], v[4:7]
	v_mfma_f32_16x16x32_bf16 v[8:11], v[214:217], v[176:179], v[8:11]
	v_mfma_f32_16x16x32_bf16 v[12:15], v[222:225], v[176:179], v[12:15]
	v_mfma_f32_16x16x32_bf16 v[16:19], v[204:207], v[180:183], v[16:19]
	v_mfma_f32_16x16x32_bf16 v[20:23], v[210:213], v[180:183], v[20:23]
	v_mfma_f32_16x16x32_bf16 v[24:27], v[214:217], v[180:183], v[24:27]
	v_mfma_f32_16x16x32_bf16 v[28:31], v[222:225], v[180:183], v[28:31]
	v_mfma_f32_16x16x32_bf16 v[32:35], v[204:207], v[184:187], v[32:35]
	v_mfma_f32_16x16x32_bf16 v[36:39], v[210:213], v[184:187], v[36:39]
	v_mfma_f32_16x16x32_bf16 v[40:43], v[214:217], v[184:187], v[40:43]
	v_mfma_f32_16x16x32_bf16 v[44:47], v[222:225], v[184:187], v[44:47]
	v_mfma_f32_16x16x32_bf16 v[48:51], v[204:207], v[188:191], v[48:51]
	v_mfma_f32_16x16x32_bf16 v[52:55], v[210:213], v[188:191], v[52:55]
	v_mfma_f32_16x16x32_bf16 v[56:59], v[214:217], v[188:191], v[56:59]
	v_mfma_f32_16x16x32_bf16 v[60:63], v[222:225], v[188:191], v[60:63]
	ds_read_b128 v[176:179], v221 offset:1024
	ds_read_b128 v[180:183], v221 offset:3072
	ds_read_b128 v[184:187], v221 offset:5120
	ds_read_b128 v[188:191], v221 offset:7168
	ds_read_b128 v[64:67], v226 offset:33792
	ds_read_b128 v[68:71], v226 offset:35840
	ds_read_b128 v[72:75], v226 offset:37888
	ds_read_b128 v[76:79], v226 offset:39936
	s_waitcnt lgkmcnt(8)
	v_mfma_f32_16x16x32_bf16 v[140:143], v[204:207], v[144:147], v[140:143]
	v_mfma_f32_16x16x32_bf16 v[136:139], v[210:213], v[144:147], v[136:139]
	v_mfma_f32_16x16x32_bf16 v[132:135], v[214:217], v[144:147], v[132:135]
	v_mfma_f32_16x16x32_bf16 v[128:131], v[222:225], v[144:147], v[128:131]
	v_mfma_f32_16x16x32_bf16 v[124:127], v[204:207], v[148:151], v[124:127]
	v_mfma_f32_16x16x32_bf16 v[120:123], v[210:213], v[148:151], v[120:123]
	v_mfma_f32_16x16x32_bf16 v[116:119], v[214:217], v[148:151], v[116:119]
	v_mfma_f32_16x16x32_bf16 v[112:115], v[222:225], v[148:151], v[112:115]
	v_mfma_f32_16x16x32_bf16 v[108:111], v[204:207], v[152:155], v[108:111]
	v_mfma_f32_16x16x32_bf16 v[104:107], v[210:213], v[152:155], v[104:107]
	v_mfma_f32_16x16x32_bf16 v[100:103], v[214:217], v[152:155], v[100:103]
	v_mfma_f32_16x16x32_bf16 v[96:99], v[222:225], v[152:155], v[96:99]
	v_mfma_f32_16x16x32_bf16 v[92:95], v[204:207], v[156:159], v[92:95]
	v_mfma_f32_16x16x32_bf16 v[88:91], v[210:213], v[156:159], v[88:91]
	v_mfma_f32_16x16x32_bf16 v[84:87], v[214:217], v[156:159], v[84:87]
	v_mfma_f32_16x16x32_bf16 v[80:83], v[222:225], v[156:159], v[80:83]
	ds_read_b128 v[156:159], v221 offset:9216
	ds_read_b128 v[152:155], v221 offset:11264
	ds_read_b128 v[148:151], v221 offset:13312
	ds_read_b128 v[144:147], v221 offset:15360
	s_waitcnt lgkmcnt(4)
	v_mfma_f32_16x16x32_bf16 v[0:3], v[64:67], v[176:179], v[0:3]
	v_mfma_f32_16x16x32_bf16 v[4:7], v[68:71], v[176:179], v[4:7]
	v_mfma_f32_16x16x32_bf16 v[8:11], v[72:75], v[176:179], v[8:11]
	v_mfma_f32_16x16x32_bf16 v[12:15], v[76:79], v[176:179], v[12:15]
	v_mfma_f32_16x16x32_bf16 v[16:19], v[64:67], v[180:183], v[16:19]
	v_mfma_f32_16x16x32_bf16 v[20:23], v[68:71], v[180:183], v[20:23]
	v_mfma_f32_16x16x32_bf16 v[24:27], v[72:75], v[180:183], v[24:27]
	v_mfma_f32_16x16x32_bf16 v[28:31], v[76:79], v[180:183], v[28:31]
	v_mfma_f32_16x16x32_bf16 v[32:35], v[64:67], v[184:187], v[32:35]
	v_mfma_f32_16x16x32_bf16 v[36:39], v[68:71], v[184:187], v[36:39]
	v_mfma_f32_16x16x32_bf16 v[40:43], v[72:75], v[184:187], v[40:43]
	v_mfma_f32_16x16x32_bf16 v[44:47], v[76:79], v[184:187], v[44:47]
	v_mfma_f32_16x16x32_bf16 v[48:51], v[64:67], v[188:191], v[48:51]
	v_mfma_f32_16x16x32_bf16 v[52:55], v[68:71], v[188:191], v[52:55]
	v_mfma_f32_16x16x32_bf16 v[56:59], v[72:75], v[188:191], v[56:59]
	v_mfma_f32_16x16x32_bf16 v[60:63], v[76:79], v[188:191], v[60:63]
	s_waitcnt lgkmcnt(0)
	s_add_u32 s52, s52, 0x80
	s_addc_u32 s53, s53, 0
	s_add_u32 s64, s64, 0x80
	s_addc_u32 s65, s65, 0
	s_add_u32 s4, s4, 0x80
	s_addc_u32 s5, s5, 0
	s_add_i32 s43, s43, 0x10000
	s_cmpk_eq_i32 s4, 0x1f00
	s_waitcnt vmcnt(0)
	s_barrier
; #define G_STAGE_A(Ap, buf, kt) do { const char* ab_ = (const char*)(Ap) + (size_t)(kt) * 128; \
;       _Pragma("unroll") for (int i = 0; i < 4; ++i) \
;         __builtin_amdgcn_global_load_lds((const unsigned*)(ab_ + soff[i]), (LDSP unsigned*)(G_SA(buf) + wid * 1024 + i * 8192), 16, 0, 0); } while (0)
; #define G_STAGE_B(Bp, buf, kt) do { const char* bb_ = (const char*)(Bp) + (size_t)(kt) * 128; \
;       _Pragma("unroll") for (int i = 0; i < 4; ++i) \
;         __builtin_amdgcn_global_load_lds((const unsigned*)(bb_ + soff[i]), (LDSP unsigned*)(G_SB(buf) + wid * 1024 + i * 8192), 16, 0, 0); } while (0)
; #define G_RDA(AF, buf, ks, mh) do { _Pragma("unroll") for (int m = 0; m < 4; ++m) AF[m] = *(const LDSP bf16x8*)(G_SA(buf) + aoff + ((mh) * 4 + m) * 2048 + (ks) * 1024); } while (0)
; #define G_RDB(BF, buf, ks) do { _Pragma("unroll") for (int n = 0; n < 4; ++n) BF[n] = *(const LDSP bf16x8*)(G_SB(buf) + boff + n * 2048 + (ks) * 1024); } while (0)
; #define G_MMA(AF, BF, mh) do { __builtin_amdgcn_s_setprio(1); \
;             _Pragma("unroll") for (int m = 0; m < 4; ++m) _Pragma("unroll") for (int n = 0; n < 4; ++n) \
;                 acc[(mh) * 4 + m][n] = __builtin_amdgcn_mfma_f32_16x16x32_bf16(BF[n], AF[m], acc[(mh) * 4 + m][n], 0, 0, 0); \
;             __builtin_amdgcn_s_setprio(0); } while (0)
; #define G_SB0() __builtin_amdgcn_sched_barrier(0)
; template <int EK>
; DI void gemm_stream(const Params& p, int l, const bf16_t* __restrict__ A, const bf16_t* __restrict__ Bt, int M, int N, int K, ldsp_t shm) {
;     ...
;         for (int t = 0; t < nt; ++t) {
;             const int cur = t & 1;
;             G_RDA(Aa, cur, 0, 0); G_RDB(Bk0, cur, 0);
;             if (t + 1 < nt) G_STAGE_B(Bb, cur ^ 1, t + 1);
;             else if (has_next) G_STAGE_B(Bb2, cur ^ 1, 0);
;             G_SB0();
;             if (t > 0) G_MMA(Ab_, Bk1, 1);
;             G_SB0();
;             if (t + 1 < nt) G_STAGE_A(Ab, cur ^ 1, t + 1);
;             else if (has_next) G_STAGE_A(Ab2, cur ^ 1, 0);
	s_cbranch_scc0 .LBB0_191
	v_readlane_b32 s52, v255, 12
	v_readlane_b32 s53, v255, 13
	v_readlane_b32 s64, v255, 14
	v_readlane_b32 s65, v255, 15
	v_readlane_b32 s30, v255, 16
	v_add_u32_e32 v160, 0x10000, v218
	v_add_u32_e32 v161, 0x10800, v218
	ds_read_b128 v[188:191], v160
	ds_read_b128 v[180:183], v161
	v_add_u32_e32 v160, 0x11000, v218
	v_add_u32_e32 v161, 0x11800, v218
	ds_read_b128 v[184:187], v160
	ds_read_b128 v[176:179], v161
	v_or_b32_e32 v160, 0x18000, v219
	v_add_u32_e32 v164, 0x18800, v219
	v_add_u32_e32 v168, 0x19000, v219
	v_add_u32_e32 v172, 0x19800, v219
	ds_read_b128 v[160:163], v160
	ds_read_b128 v[164:167], v164
	ds_read_b128 v[168:171], v168
	ds_read_b128 v[172:175], v172
	s_ashr_i32 s47, s46, 31
	v_cndmask_b32_e64 v200, 0, 1, s[34:35]
	v_cmp_ne_u32_e64 s[4:5], 1, v200
	s_andn2_b64 vcc, exec, s[34:35]
	s_lshl_b64 s[50:51], s[46:47], 21
	s_cbranch_vccnz .LBB0_194
	s_add_u32 s6, s9, s50
	s_addc_u32 s7, s31, s51
	v_add_u32_e32 v212, 0x8000, v220
	v_lshl_add_u64 v[200:201], s[6:7], 0, v[192:193]
	v_lshl_add_u64 v[204:205], s[6:7], 0, v[194:195]
	v_lshl_add_u64 v[206:207], s[6:7], 0, v[196:197]
	v_lshl_add_u64 v[210:211], s[6:7], 0, v[198:199]
	v_add_u32_e32 v215, 0xa000, v220
	v_readfirstlane_b32 s6, v212
	v_add_u32_e32 v214, 0xc000, v220
	s_mov_b32 m0, s6
	v_readfirstlane_b32 s6, v215
	v_add_u32_e32 v213, 0xe000, v220
	global_load_lds_dwordx4 v[200:201], off
	s_mov_b32 m0, s6
	v_readfirstlane_b32 s6, v214
	global_load_lds_dwordx4 v[204:205], off
	s_mov_b32 m0, s6
	v_readfirstlane_b32 s6, v213
	global_load_lds_dwordx4 v[206:207], off
	s_mov_b32 m0, s6
	s_nop 0
	global_load_lds_dwordx4 v[210:211], off

; #define WAIT_V0() asm volatile("s_waitcnt vmcnt(0)" ::: "memory")
; #define G_STAGE_A(Ap, buf, kt) do { const char* ab_ = (const char*)(Ap) + (size_t)(kt) * 128; \
;       _Pragma("unroll") for (int i = 0; i < 4; ++i) \
;         __builtin_amdgcn_global_load_lds((const unsigned*)(ab_ + soff[i]), (LDSP unsigned*)(G_SA(buf) + wid * 1024 + i * 8192), 16, 0, 0); } while (0)
; #define G_STAGE_B(Bp, buf, kt) do { const char* bb_ = (const char*)(Bp) + (size_t)(kt) * 128; \
;       _Pragma("unroll") for (int i = 0; i < 4; ++i) \
;         __builtin_amdgcn_global_load_lds((const unsigned*)(bb_ + soff[i]), (LDSP unsigned*)(G_SB(buf) + wid * 1024 + i * 8192), 16, 0, 0); } while (0)
; #define G_RDA(AF, buf, ks, mh) do { _Pragma("unroll") for (int m = 0; m < 4; ++m) AF[m] = *(const LDSP bf16x8*)(G_SA(buf) + aoff + ((mh) * 4 + m) * 2048 + (ks) * 1024); } while (0)
; #define G_RDB(BF, buf, ks) do { _Pragma("unroll") for (int n = 0; n < 4; ++n) BF[n] = *(const LDSP bf16x8*)(G_SB(buf) + boff + n * 2048 + (ks) * 1024); } while (0)
; #define G_MMA(AF, BF, mh) do { __builtin_amdgcn_s_setprio(1); \
;             _Pragma("unroll") for (int m = 0; m < 4; ++m) _Pragma("unroll") for (int n = 0; n < 4; ++n) \
;                 acc[(mh) * 4 + m][n] = __builtin_amdgcn_mfma_f32_16x16x32_bf16(BF[n], AF[m], acc[(mh) * 4 + m][n], 0, 0, 0); \
;             __builtin_amdgcn_s_setprio(0); } while (0)
; template <int EK>
; DI void gemm_stream(const Params& p, int l, const bf16_t* __restrict__ A, const bf16_t* __restrict__ Bt, int M, int N, int K, ldsp_t shm) {
;     ...
;         for (int t = 0; t < nt; ++t) {
;             const int cur = t & 1;
;             G_RDA(Aa, cur, 0, 0); G_RDB(Bk0, cur, 0);
;             if (t + 1 < nt) G_STAGE_B(Bb, cur ^ 1, t + 1);
;             else if (has_next) G_STAGE_B(Bb2, cur ^ 1, 0);
;             G_SB0();
;             if (t > 0) G_MMA(Ab_, Bk1, 1);
;             G_SB0();
;             if (t + 1 < nt) G_STAGE_A(Ab, cur ^ 1, t + 1);
;             else if (has_next) G_STAGE_A(Ab2, cur ^ 1, 0);
;             G_RDA(Ab_, cur, 0, 1);
;             G_MMA(Aa, Bk0, 0); G_SB0();
;             G_RDA(Aa, cur, 1, 0); G_RDB(Bk1, cur, 1);
;             G_MMA(Ab_, Bk0, 1); G_SB0();
;             G_RDA(Ab_, cur, 1, 1);
;             G_MMA(Aa, Bk1, 0); G_SB0();
;             asm volatile("s_waitcnt lgkmcnt(0)" ::: "memory");
;             WAIT_V0(); __syncthreads();
;         }
.LBB0_264:
	s_and_b32 s9, s8, 0x10000
	v_add_u32_e32 v221, s9, v218
	v_or_b32_e32 v226, s9, v219
	s_xor_b32 s9, s9, 0x10000
	s_add_u32 s9, s9, s30
	ds_read_b128 v[176:179], v221
	ds_read_b128 v[180:183], v221 offset:2048
	ds_read_b128 v[184:187], v221 offset:4096
	ds_read_b128 v[188:191], v221 offset:6144
	s_add_u32 m0, s9, 0x8000
	ds_read_b128 v[204:207], v226 offset:32768
	global_load_lds_dwordx4 v168, s[64:65]
	s_add_u32 m0, s9, 0xa000
	ds_read_b128 v[210:213], v226 offset:34816
	global_load_lds_dwordx4 v170, s[64:65]
	s_add_u32 m0, s9, 0xc000
	ds_read_b128 v[214:217], v226 offset:36864
	global_load_lds_dwordx4 v172, s[64:65]
	s_add_u32 m0, s9, 0xe000
	ds_read_b128 v[222:225], v226 offset:38912
	global_load_lds_dwordx4 v174, s[64:65]
	v_mfma_f32_16x16x32_bf16 v[128:131], v[64:67], v[156:159], v[128:131]
	v_mfma_f32_16x16x32_bf16 v[124:127], v[68:71], v[156:159], v[124:127]
	v_mfma_f32_16x16x32_bf16 v[120:123], v[76:79], v[156:159], v[120:123]
	v_mfma_f32_16x16x32_bf16 v[116:119], v[72:75], v[156:159], v[116:119]
	v_mfma_f32_16x16x32_bf16 v[112:115], v[64:67], v[152:155], v[112:115]
	v_mfma_f32_16x16x32_bf16 v[108:111], v[68:71], v[152:155], v[108:111]
	v_mfma_f32_16x16x32_bf16 v[104:107], v[76:79], v[152:155], v[104:107]
	v_mfma_f32_16x16x32_bf16 v[100:103], v[72:75], v[152:155], v[100:103]
	v_mfma_f32_16x16x32_bf16 v[96:99], v[64:67], v[148:151], v[96:99]
	v_mfma_f32_16x16x32_bf16 v[92:95], v[68:71], v[148:151], v[92:95]
	v_mfma_f32_16x16x32_bf16 v[88:91], v[76:79], v[148:151], v[88:91]
	v_mfma_f32_16x16x32_bf16 v[84:87], v[72:75], v[148:151], v[84:87]
	v_mfma_f32_16x16x32_bf16 v[132:135], v[64:67], v[144:147], v[132:135]
	v_mfma_f32_16x16x32_bf16 v[136:139], v[68:71], v[144:147], v[136:139]
	v_mfma_f32_16x16x32_bf16 v[140:143], v[76:79], v[144:147], v[140:143]
	v_mfma_f32_16x16x32_bf16 v[80:83], v[72:75], v[144:147], v[80:83]
	s_add_u32 m0, s9, 0x0
	s_nop 0
	global_load_lds_dwordx4 v168, s[52:53]
	s_add_u32 m0, s9, 0x2000
	s_nop 0
	global_load_lds_dwordx4 v170, s[52:53]
	s_add_u32 m0, s9, 0x4000
	s_nop 0
	global_load_lds_dwordx4 v172, s[52:53]
	s_add_u32 m0, s9, 0x6000
	s_nop 0
	global_load_lds_dwordx4 v174, s[52:53]
	ds_read_b128 v[144:147], v221 offset:8192
	ds_read_b128 v[148:151], v221 offset:10240
	ds_read_b128 v[152:155], v221 offset:12288
	ds_read_b128 v[156:159], v221 offset:14336
	s_waitcnt lgkmcnt(4)
	v_mfma_f32_16x16x32_bf16 v[0:3], v[204:207], v[176:179], v[0:3]
	v_mfma_f32_16x16x32_bf16 v[4:7], v[210:213], v[176:179], v[4:7]
	v_mfma_f32_16x16x32_bf16 v[8:11], v[214:217], v[176:179], v[8:11]
	v_mfma_f32_16x16x32_bf16 v[12:15], v[222:225], v[176:179], v[12:15]
	v_mfma_f32_16x16x32_bf16 v[16:19], v[204:207], v[180:183], v[16:19]
	v_mfma_f32_16x16x32_bf16 v[20:23], v[210:213], v[180:183], v[20:23]
	v_mfma_f32_16x16x32_bf16 v[24:27], v[214:217], v[180:183], v[24:27]
	v_mfma_f32_16x16x32_bf16 v[28:31], v[222:225], v[180:183], v[28:31]
	v_mfma_f32_16x16x32_bf16 v[32:35], v[204:207], v[184:187], v[32:35]
	v_mfma_f32_16x16x32_bf16 v[36:39], v[210:213], v[184:187], v[36:39]
	v_mfma_f32_16x16x32_bf16 v[40:43], v[214:217], v[184:187], v[40:43]
	v_mfma_f32_16x16x32_bf16 v[44:47], v[222:225], v[184:187], v[44:47]
	v_mfma_f32_16x16x32_bf16 v[48:51], v[204:207], v[188:191], v[48:51]
	v_mfma_f32_16x16x32_bf16 v[52:55], v[210:213], v[188:191], v[52:55]
	v_mfma_f32_16x16x32_bf16 v[56:59], v[214:217], v[188:191], v[56:59]
	v_mfma_f32_16x16x32_bf16 v[60:63], v[222:225], v[188:191], v[60:63]
	ds_read_b128 v[176:179], v221 offset:1024
	ds_read_b128 v[180:183], v221 offset:3072
	ds_read_b128 v[184:187], v221 offset:5120
	ds_read_b128 v[188:191], v221 offset:7168
	ds_read_b128 v[64:67], v226 offset:33792
	ds_read_b128 v[68:71], v226 offset:35840
	ds_read_b128 v[76:79], v226 offset:37888
	ds_read_b128 v[72:75], v226 offset:39936
	s_waitcnt lgkmcnt(8)
	v_mfma_f32_16x16x32_bf16 v[128:131], v[204:207], v[144:147], v[128:131]
	v_mfma_f32_16x16x32_bf16 v[124:127], v[210:213], v[144:147], v[124:127]
	v_mfma_f32_16x16x32_bf16 v[120:123], v[214:217], v[144:147], v[120:123]
	v_mfma_f32_16x16x32_bf16 v[116:119], v[222:225], v[144:147], v[116:119]
	v_mfma_f32_16x16x32_bf16 v[112:115], v[204:207], v[148:151], v[112:115]
	v_mfma_f32_16x16x32_bf16 v[108:111], v[210:213], v[148:151], v[108:111]
	v_mfma_f32_16x16x32_bf16 v[104:107], v[214:217], v[148:151], v[104:107]
	v_mfma_f32_16x16x32_bf16 v[100:103], v[222:225], v[148:151], v[100:103]
	v_mfma_f32_16x16x32_bf16 v[96:99], v[204:207], v[152:155], v[96:99]
	v_mfma_f32_16x16x32_bf16 v[92:95], v[210:213], v[152:155], v[92:95]
	v_mfma_f32_16x16x32_bf16 v[88:91], v[214:217], v[152:155], v[88:91]
	v_mfma_f32_16x16x32_bf16 v[84:87], v[222:225], v[152:155], v[84:87]
	v_mfma_f32_16x16x32_bf16 v[132:135], v[204:207], v[156:159], v[132:135]
	v_mfma_f32_16x16x32_bf16 v[136:139], v[210:213], v[156:159], v[136:139]
	v_mfma_f32_16x16x32_bf16 v[140:143], v[214:217], v[156:159], v[140:143]
	v_mfma_f32_16x16x32_bf16 v[80:83], v[222:225], v[156:159], v[80:83]
	ds_read_b128 v[156:159], v221 offset:9216
	ds_read_b128 v[152:155], v221 offset:11264
	ds_read_b128 v[148:151], v221 offset:13312
	ds_read_b128 v[144:147], v221 offset:15360
	s_waitcnt lgkmcnt(4)
	v_mfma_f32_16x16x32_bf16 v[0:3], v[64:67], v[176:179], v[0:3]
	v_mfma_f32_16x16x32_bf16 v[4:7], v[68:71], v[176:179], v[4:7]
	v_mfma_f32_16x16x32_bf16 v[8:11], v[76:79], v[176:179], v[8:11]
	v_mfma_f32_16x16x32_bf16 v[12:15], v[72:75], v[176:179], v[12:15]
	v_mfma_f32_16x16x32_bf16 v[16:19], v[64:67], v[180:183], v[16:19]
	v_mfma_f32_16x16x32_bf16 v[20:23], v[68:71], v[180:183], v[20:23]
	v_mfma_f32_16x16x32_bf16 v[24:27], v[76:79], v[180:183], v[24:27]
	v_mfma_f32_16x16x32_bf16 v[28:31], v[72:75], v[180:183], v[28:31]
	v_mfma_f32_16x16x32_bf16 v[32:35], v[64:67], v[184:187], v[32:35]
	v_mfma_f32_16x16x32_bf16 v[36:39], v[68:71], v[184:187], v[36:39]
	v_mfma_f32_16x16x32_bf16 v[40:43], v[76:79], v[184:187], v[40:43]
	v_mfma_f32_16x16x32_bf16 v[44:47], v[72:75], v[184:187], v[44:47]
	v_mfma_f32_16x16x32_bf16 v[48:51], v[64:67], v[188:191], v[48:51]
	v_mfma_f32_16x16x32_bf16 v[52:55], v[68:71], v[188:191], v[52:55]
	v_mfma_f32_16x16x32_bf16 v[56:59], v[76:79], v[188:191], v[56:59]
	v_mfma_f32_16x16x32_bf16 v[60:63], v[72:75], v[188:191], v[60:63]
	s_waitcnt lgkmcnt(0)
	s_add_u32 s52, s52, 0x80
	s_addc_u32 s53, s53, 0
	s_add_u32 s64, s64, 0x80
	s_addc_u32 s65, s65, 0
	s_add_u32 s4, s4, 0x80
	s_addc_u32 s5, s5, 0
	s_add_i32 s8, s8, 0x10000
	s_cmpk_eq_i32 s4, 0x700
	s_waitcnt vmcnt(0)
	s_barrier
; #define G_STAGE_A(Ap, buf, kt) do { const char* ab_ = (const char*)(Ap) + (size_t)(kt) * 128; \
;       _Pragma("unroll") for (int i = 0; i < 4; ++i) \
;         __builtin_amdgcn_global_load_lds((const unsigned*)(ab_ + soff[i]), (LDSP unsigned*)(G_SA(buf) + wid * 1024 + i * 8192), 16, 0, 0); } while (0)
; #define G_STAGE_B(Bp, buf, kt) do { const char* bb_ = (const char*)(Bp) + (size_t)(kt) * 128; \
;       _Pragma("unroll") for (int i = 0; i < 4; ++i) \
;         __builtin_amdgcn_global_load_lds((const unsigned*)(bb_ + soff[i]), (LDSP unsigned*)(G_SB(buf) + wid * 1024 + i * 8192), 16, 0, 0); } while (0)
; #define G_RDA(AF, buf, ks, mh) do { _Pragma("unroll") for (int m = 0; m < 4; ++m) AF[m] = *(const LDSP bf16x8*)(G_SA(buf) + aoff + ((mh) * 4 + m) * 2048 + (ks) * 1024); } while (0)
; #define G_RDB(BF, buf, ks) do { _Pragma("unroll") for (int n = 0; n < 4; ++n) BF[n] = *(const LDSP bf16x8*)(G_SB(buf) + boff + n * 2048 + (ks) * 1024); } while (0)
; #define G_MMA(AF, BF, mh) do { __builtin_amdgcn_s_setprio(1); \
;             _Pragma("unroll") for (int m = 0; m < 4; ++m) _Pragma("unroll") for (int n = 0; n < 4; ++n) \
;                 acc[(mh) * 4 + m][n] = __builtin_amdgcn_mfma_f32_16x16x32_bf16(BF[n], AF[m], acc[(mh) * 4 + m][n], 0, 0, 0); \
;             __builtin_amdgcn_s_setprio(0); } while (0)
; #define G_SB0() __builtin_amdgcn_sched_barrier(0)
; template <int EK>
; DI void gemm_stream(const Params& p, int l, const bf16_t* __restrict__ A, const bf16_t* __restrict__ Bt, int M, int N, int K, ldsp_t shm) {
;     ...
;         for (int t = 0; t < nt; ++t) {
;             const int cur = t & 1;
;             G_RDA(Aa, cur, 0, 0); G_RDB(Bk0, cur, 0);
;             if (t + 1 < nt) G_STAGE_B(Bb, cur ^ 1, t + 1);
;             else if (has_next) G_STAGE_B(Bb2, cur ^ 1, 0);
;             G_SB0();
;             if (t > 0) G_MMA(Ab_, Bk1, 1);
;             G_SB0();
;             if (t + 1 < nt) G_STAGE_A(Ab, cur ^ 1, t + 1);
;             else if (has_next) G_STAGE_A(Ab2, cur ^ 1, 0);
	s_cbranch_scc0 .LBB0_264
	v_readlane_b32 s52, v255, 12
	v_readlane_b32 s53, v255, 13
	v_readlane_b32 s64, v255, 14
	v_readlane_b32 s65, v255, 15
	v_readlane_b32 s30, v255, 16
	v_add_u32_e32 v160, 0x10000, v218
	v_add_u32_e32 v161, 0x10800, v218
	ds_read_b128 v[188:191], v160
	ds_read_b128 v[180:183], v161
	v_add_u32_e32 v160, 0x11000, v218
	v_add_u32_e32 v161, 0x11800, v218
	ds_read_b128 v[184:187], v160
	ds_read_b128 v[176:179], v161
	v_or_b32_e32 v160, 0x18000, v219
	v_add_u32_e32 v164, 0x18800, v219
	v_add_u32_e32 v168, 0x19000, v219
	v_add_u32_e32 v172, 0x19800, v219
	ds_read_b128 v[160:163], v160
	ds_read_b128 v[164:167], v164
	ds_read_b128 v[168:171], v168
	ds_read_b128 v[172:175], v172
	s_ashr_i32 s43, s42, 31
	v_cndmask_b32_e64 v200, 0, 1, s[6:7]
	v_cmp_ne_u32_e64 s[4:5], 1, v200
	s_andn2_b64 vcc, exec, s[6:7]
	s_lshl_b64 s[46:47], s[42:43], 19
	s_cbranch_vccnz .LBB0_267
	s_add_u32 s6, s14, s46
	s_addc_u32 s7, s15, s47
	v_add_u32_e32 v212, 0x8000, v220
	v_lshl_add_u64 v[200:201], s[6:7], 0, v[192:193]
	v_lshl_add_u64 v[204:205], s[6:7], 0, v[194:195]
	v_lshl_add_u64 v[206:207], s[6:7], 0, v[196:197]
	v_lshl_add_u64 v[210:211], s[6:7], 0, v[198:199]
	v_add_u32_e32 v215, 0xa000, v220
	v_readfirstlane_b32 s6, v212
	v_add_u32_e32 v214, 0xc000, v220
	s_mov_b32 m0, s6
	v_readfirstlane_b32 s6, v215
	v_add_u32_e32 v213, 0xe000, v220
	global_load_lds_dwordx4 v[200:201], off
	s_mov_b32 m0, s6
	v_readfirstlane_b32 s6, v214
	global_load_lds_dwordx4 v[204:205], off
	s_mov_b32 m0, s6
	v_readfirstlane_b32 s6, v213
	global_load_lds_dwordx4 v[206:207], off
	s_mov_b32 m0, s6
	s_nop 0
	global_load_lds_dwordx4 v[210:211], off
